# in-projection decode rows in one pass: all 8 row tiles of a 32-column group per workgroup, weight slice loaded once, 40 loads in flight
# speedup vs baseline: 1.0100x; 1.0100x over previous
.LBB0_294:
	s_cmp_eq_u32 s101, 2
	s_cbranch_scc1 .Lin_seam2
	v_mov_b32_e32 v0, v176
	s_mul_i32 s2, s54, 8
	s_waitcnt vmcnt(0)
	s_barrier
	s_cmpk_gt_i32 s2, 0x5ff
	v_readfirstlane_b32 s0, v0
	s_cbranch_scc1 .LBB0_307
	v_lshrrev_b32_e32 v1, 1, v0
	v_and_b32_e32 v16, 24, v1
	v_and_b32_e32 v1, 63, v0
	s_ashr_i32 s3, s0, 6
	v_lshl_add_u32 v17, v1, 4, 0
	v_and_b32_e32 v6, 15, v0
	v_lshlrev_b32_e32 v1, 1, v0
	v_and_b32_e32 v0, 3, v0
	v_and_or_b32 v1, v1, 24, v0
	s_lshl_b32 s0, s3, 7
	s_lshl_b32 s8, s3, 11
	v_or_b32_e32 v0, s0, v16
	v_lshlrev_b32_e32 v2, 11, v1
	v_lshl_add_u32 v1, v1, 10, s0
	s_cmp_lt_i32 s3, 8
	v_readlane_b32 s16, v252, 0
	v_lshlrev_b32_e32 v0, 1, v0
	s_movk_i32 s1, 0x2000
	v_or_b32_e32 v1, v1, v16
	s_cselect_b64 s[4:5], -1, 0
	s_lshl_b32 s12, s3, 14
	v_readlane_b32 s22, v252, 6
	v_add3_u32 v0, v0, v2, s1
	v_lshlrev_b32_e32 v2, 1, v1
	v_lshl_add_u32 v1, v6, 10, s0
	v_readlane_b32 s23, v252, 7
	s_add_u32 s0, s22, 0x2120000
	s_addc_u32 s1, s23, 0
	s_add_u32 s14, s22, 0x5180000
	s_addc_u32 s15, s23, 0
	s_mul_i32 s6, s54, 0x80
	s_lshl_b32 s7, s3, 4
	v_or_b32_e32 v1, v1, v16
	v_mov_b32_e32 v7, 0
	v_readlane_b32 s17, v252, 1
	v_readlane_b32 s18, v252, 2
	v_readlane_b32 s19, v252, 3
	v_readlane_b32 s20, v252, 4
	v_readlane_b32 s21, v252, 5
	v_or_b32_e32 v18, 0x4000, v6
	s_add_i32 s16, s6, s7
	s_mul_i32 s6, s54, 32
	v_cndmask_b32_e64 v6, 0, 1, s[4:5]
	v_lshlrev_b32_e32 v4, 1, v1
	v_mov_b32_e32 v5, v7
	v_mov_b32_e32 v3, v7
	v_mov_b32_e32 v1, v7
	s_mul_i32 s13, s86, 8
	s_mul_i32 s17, s86, 0x80
	s_lshl_b32 s18, s3, 2
	s_add_i32 s19, s6, 8
	s_mul_i32 s20, s86, 32
	s_mul_i32 s21, s54, 0xc000
	s_mul_i32 s22, s86, 0xc000
	s_mov_b64 s[6:7], 0x2000000
	s_brev_b32 s23, 64
	v_add_u32_e32 v19, s8, v17
	v_cmp_ne_u32_e64 s[4:5], 1, v6
	s_movk_i32 s24, 0x3ff
	s_movk_i32 s25, 0xfa00
	s_mov_b32 s26, 0x1020000
	v_mov_b32_e32 v20, 0x3db504f3
	s_branch .LBB0_298

.LBB0_298:
	v_readlane_b32 s40, v252, 4
	v_readlane_b32 s41, v252, 5
	s_lshl_b32 s10, s2, 13
	s_add_u32 s8, s40, 0x2000000
	s_addc_u32 s9, s41, 0
	s_add_u32 s10, s64, s10
	s_addc_u32 s11, s65, 0
	v_mov_b32_e32 v34, v4
	v_add_u32_e32 v35, 0x8000, v4
	v_add_u32_e32 v36, 0x10000, v4
	v_add_u32_e32 v37, 0x18000, v4
	v_add_u32_e32 v38, 0x20000, v4
	v_add_u32_e32 v39, 0x28000, v4
	v_add_u32_e32 v40, 0x30000, v4
	v_add_u32_e32 v41, 0x38000, v4
	v_add_u32_e32 v250, 0x10000, v19
	global_load_dwordx4 v[42:45], v2, s[10:11]
	global_load_dwordx4 v[46:49], v2, s[10:11] offset:64
	global_load_dwordx4 v[50:53], v2, s[10:11] offset:128
	global_load_dwordx4 v[54:57], v2, s[10:11] offset:192
	global_load_dwordx4 v[58:61], v0, s[10:11]
	global_load_dwordx4 v[62:65], v0, s[10:11] offset:64
	global_load_dwordx4 v[66:69], v0, s[10:11] offset:128
	global_load_dwordx4 v[70:73], v0, s[10:11] offset:192
	global_load_dwordx4 v[106:109], v34, s[8:9]
	global_load_dwordx4 v[110:113], v34, s[8:9] offset:64
	global_load_dwordx4 v[114:117], v34, s[8:9] offset:128
	global_load_dwordx4 v[118:121], v34, s[8:9] offset:192
	global_load_dwordx4 v[122:125], v35, s[8:9]
	global_load_dwordx4 v[126:129], v35, s[8:9] offset:64
	global_load_dwordx4 v[130:133], v35, s[8:9] offset:128
	global_load_dwordx4 v[134:137], v35, s[8:9] offset:192
	global_load_dwordx4 v[140:143], v36, s[8:9]
	global_load_dwordx4 v[144:147], v36, s[8:9] offset:64
	global_load_dwordx4 v[148:151], v36, s[8:9] offset:128
	global_load_dwordx4 v[152:155], v36, s[8:9] offset:192
	global_load_dwordx4 v[156:159], v37, s[8:9]
	global_load_dwordx4 v[160:163], v37, s[8:9] offset:64
	global_load_dwordx4 v[164:167], v37, s[8:9] offset:128
	global_load_dwordx4 v[168:171], v37, s[8:9] offset:192
	global_load_dwordx4 v[172:175], v38, s[8:9]
	global_load_dwordx4 v[178:181], v38, s[8:9] offset:64
	global_load_dwordx4 v[182:185], v38, s[8:9] offset:128
	global_load_dwordx4 v[186:189], v38, s[8:9] offset:192
	global_load_dwordx4 v[190:193], v39, s[8:9]
	global_load_dwordx4 v[194:197], v39, s[8:9] offset:64
	global_load_dwordx4 v[198:201], v39, s[8:9] offset:128
	global_load_dwordx4 v[202:205], v39, s[8:9] offset:192
	global_load_dwordx4 v[206:209], v40, s[8:9]
	global_load_dwordx4 v[210:213], v40, s[8:9] offset:64
	global_load_dwordx4 v[214:217], v40, s[8:9] offset:128
	global_load_dwordx4 v[218:221], v40, s[8:9] offset:192
	global_load_dwordx4 v[222:225], v41, s[8:9]
	global_load_dwordx4 v[226:229], v41, s[8:9] offset:64
	global_load_dwordx4 v[230:233], v41, s[8:9] offset:128
	global_load_dwordx4 v[234:237], v41, s[8:9] offset:192
	s_and_b64 vcc, exec, s[4:5]
	s_waitcnt vmcnt(28)
	v_mfma_f32_16x16x32_bf16 v[74:77], v[42:45], v[106:109], 0
	v_mfma_f32_16x16x32_bf16 v[78:81], v[58:61], v[106:109], 0
	v_mfma_f32_16x16x32_bf16 v[74:77], v[46:49], v[110:113], v[74:77]
	v_mfma_f32_16x16x32_bf16 v[78:81], v[62:65], v[110:113], v[78:81]
	v_mfma_f32_16x16x32_bf16 v[74:77], v[50:53], v[114:117], v[74:77]
	v_mfma_f32_16x16x32_bf16 v[78:81], v[66:69], v[114:117], v[78:81]
	v_mfma_f32_16x16x32_bf16 v[74:77], v[54:57], v[118:121], v[74:77]
	v_mfma_f32_16x16x32_bf16 v[78:81], v[70:73], v[118:121], v[78:81]
	s_waitcnt vmcnt(24)
	v_mfma_f32_16x16x32_bf16 v[82:85], v[42:45], v[122:125], 0
	v_mfma_f32_16x16x32_bf16 v[86:89], v[58:61], v[122:125], 0
	v_mfma_f32_16x16x32_bf16 v[82:85], v[46:49], v[126:129], v[82:85]
	v_mfma_f32_16x16x32_bf16 v[86:89], v[62:65], v[126:129], v[86:89]
	v_mfma_f32_16x16x32_bf16 v[82:85], v[50:53], v[130:133], v[82:85]
	v_mfma_f32_16x16x32_bf16 v[86:89], v[66:69], v[130:133], v[86:89]
	v_mfma_f32_16x16x32_bf16 v[82:85], v[54:57], v[134:137], v[82:85]
	v_mfma_f32_16x16x32_bf16 v[86:89], v[70:73], v[134:137], v[86:89]
	s_waitcnt vmcnt(20)
	v_mfma_f32_16x16x32_bf16 v[90:93], v[42:45], v[140:143], 0
	v_mfma_f32_16x16x32_bf16 v[94:97], v[58:61], v[140:143], 0
	v_mfma_f32_16x16x32_bf16 v[90:93], v[46:49], v[144:147], v[90:93]
	v_mfma_f32_16x16x32_bf16 v[94:97], v[62:65], v[144:147], v[94:97]
	v_mfma_f32_16x16x32_bf16 v[90:93], v[50:53], v[148:151], v[90:93]
	v_mfma_f32_16x16x32_bf16 v[94:97], v[66:69], v[148:151], v[94:97]
	v_mfma_f32_16x16x32_bf16 v[90:93], v[54:57], v[152:155], v[90:93]
	v_mfma_f32_16x16x32_bf16 v[94:97], v[70:73], v[152:155], v[94:97]
	s_waitcnt vmcnt(16)
	v_mfma_f32_16x16x32_bf16 v[98:101], v[42:45], v[156:159], 0
	v_mfma_f32_16x16x32_bf16 v[102:105], v[58:61], v[156:159], 0
	v_mfma_f32_16x16x32_bf16 v[98:101], v[46:49], v[160:163], v[98:101]
	v_mfma_f32_16x16x32_bf16 v[102:105], v[62:65], v[160:163], v[102:105]
	v_mfma_f32_16x16x32_bf16 v[98:101], v[50:53], v[164:167], v[98:101]
	v_mfma_f32_16x16x32_bf16 v[102:105], v[66:69], v[164:167], v[102:105]
	v_mfma_f32_16x16x32_bf16 v[98:101], v[54:57], v[168:171], v[98:101]
	v_mfma_f32_16x16x32_bf16 v[102:105], v[70:73], v[168:171], v[102:105]
	s_nop 7
	s_nop 1
	ds_write_b128 v19, v[74:77]
	ds_write_b128 v19, v[78:81] offset:1024
	ds_write_b128 v19, v[82:85] offset:16384
	ds_write_b128 v19, v[86:89] offset:17408
	ds_write_b128 v19, v[90:93] offset:32768
	ds_write_b128 v19, v[94:97] offset:33792
	ds_write_b128 v19, v[98:101] offset:49152
	ds_write_b128 v19, v[102:105] offset:50176
	s_waitcnt vmcnt(12)
	v_mfma_f32_16x16x32_bf16 v[106:109], v[42:45], v[172:175], 0
	v_mfma_f32_16x16x32_bf16 v[110:113], v[58:61], v[172:175], 0
	v_mfma_f32_16x16x32_bf16 v[106:109], v[46:49], v[178:181], v[106:109]
	v_mfma_f32_16x16x32_bf16 v[110:113], v[62:65], v[178:181], v[110:113]
	v_mfma_f32_16x16x32_bf16 v[106:109], v[50:53], v[182:185], v[106:109]
	v_mfma_f32_16x16x32_bf16 v[110:113], v[66:69], v[182:185], v[110:113]
	v_mfma_f32_16x16x32_bf16 v[106:109], v[54:57], v[186:189], v[106:109]
	v_mfma_f32_16x16x32_bf16 v[110:113], v[70:73], v[186:189], v[110:113]
	s_waitcnt vmcnt(8)
	v_mfma_f32_16x16x32_bf16 v[114:117], v[42:45], v[190:193], 0
	v_mfma_f32_16x16x32_bf16 v[118:121], v[58:61], v[190:193], 0
	v_mfma_f32_16x16x32_bf16 v[114:117], v[46:49], v[194:197], v[114:117]
	v_mfma_f32_16x16x32_bf16 v[118:121], v[62:65], v[194:197], v[118:121]
	v_mfma_f32_16x16x32_bf16 v[114:117], v[50:53], v[198:201], v[114:117]
	v_mfma_f32_16x16x32_bf16 v[118:121], v[66:69], v[198:201], v[118:121]
	v_mfma_f32_16x16x32_bf16 v[114:117], v[54:57], v[202:205], v[114:117]
	v_mfma_f32_16x16x32_bf16 v[118:121], v[70:73], v[202:205], v[118:121]
	s_waitcnt vmcnt(4)
	v_mfma_f32_16x16x32_bf16 v[122:125], v[42:45], v[206:209], 0
	v_mfma_f32_16x16x32_bf16 v[126:129], v[58:61], v[206:209], 0
	v_mfma_f32_16x16x32_bf16 v[122:125], v[46:49], v[210:213], v[122:125]
	v_mfma_f32_16x16x32_bf16 v[126:129], v[62:65], v[210:213], v[126:129]
	v_mfma_f32_16x16x32_bf16 v[122:125], v[50:53], v[214:217], v[122:125]
	v_mfma_f32_16x16x32_bf16 v[126:129], v[66:69], v[214:217], v[126:129]
	v_mfma_f32_16x16x32_bf16 v[122:125], v[54:57], v[218:221], v[122:125]
	v_mfma_f32_16x16x32_bf16 v[126:129], v[70:73], v[218:221], v[126:129]
	s_waitcnt vmcnt(0)
	v_mfma_f32_16x16x32_bf16 v[130:133], v[42:45], v[222:225], 0
	v_mfma_f32_16x16x32_bf16 v[134:137], v[58:61], v[222:225], 0
	v_mfma_f32_16x16x32_bf16 v[130:133], v[46:49], v[226:229], v[130:133]
	v_mfma_f32_16x16x32_bf16 v[134:137], v[62:65], v[226:229], v[134:137]
	v_mfma_f32_16x16x32_bf16 v[130:133], v[50:53], v[230:233], v[130:133]
	v_mfma_f32_16x16x32_bf16 v[134:137], v[66:69], v[230:233], v[134:137]
	v_mfma_f32_16x16x32_bf16 v[130:133], v[54:57], v[234:237], v[130:133]
	v_mfma_f32_16x16x32_bf16 v[134:137], v[70:73], v[234:237], v[134:137]
	s_nop 7
	s_nop 1
	ds_write_b128 v250, v[106:109]
	ds_write_b128 v250, v[110:113] offset:1024
	ds_write_b128 v250, v[114:117] offset:16384
	ds_write_b128 v250, v[118:121] offset:17408
	ds_write_b128 v250, v[122:125] offset:32768
	ds_write_b128 v250, v[126:129] offset:33792
	ds_write_b128 v250, v[130:133] offset:49152
	ds_write_b128 v250, v[134:137] offset:50176
	s_waitcnt lgkmcnt(0)
	s_barrier
	s_cbranch_vccnz .LBB0_297
	s_add_i32 s8, s3, s2
	s_cmpk_gt_i32 s8, 0x5ff
	s_cbranch_scc1 .LBB0_297
	v_add_u32_e32 v6, s12, v17
	ds_read_b128 v[8:11], v6 offset:2048
	ds_read_b128 v[12:15], v6
	ds_read_b128 v[22:25], v6 offset:1024
	ds_read_b128 v[26:29], v6 offset:3072
	ds_read_b128 v[30:33], v6 offset:4096
	s_add_i32 s28, s18, s19
	s_waitcnt lgkmcnt(3)
	v_pk_add_f32 v[14:15], v[14:15], v[10:11]
	v_pk_add_f32 v[34:35], v[12:13], v[8:9]
	ds_read_b128 v[8:11], v6 offset:5120
	s_waitcnt lgkmcnt(2)
	v_pk_add_f32 v[24:25], v[24:25], v[28:29]
	s_waitcnt lgkmcnt(1)
	v_pk_add_f32 v[28:29], v[14:15], v[32:33]
	ds_read_b128 v[12:15], v6 offset:6144
	v_pk_add_f32 v[26:27], v[22:23], v[26:27]
	v_pk_add_f32 v[30:31], v[34:35], v[30:31]
	s_waitcnt lgkmcnt(1)
	v_pk_add_f32 v[32:33], v[24:25], v[10:11]
	ds_read_b128 v[22:25], v6 offset:7168
	v_pk_add_f32 v[26:27], v[26:27], v[8:9]
	s_waitcnt lgkmcnt(1)
	v_pk_add_f32 v[28:29], v[28:29], v[14:15]
	ds_read_b128 v[8:11], v6 offset:8192
	v_pk_add_f32 v[30:31], v[30:31], v[12:13]
	ds_read_b128 v[12:15], v6 offset:9216
	s_waitcnt lgkmcnt(2)
	v_pk_add_f32 v[32:33], v[32:33], v[24:25]
	v_pk_add_f32 v[26:27], v[26:27], v[22:23]
	ds_read_b128 v[22:25], v6 offset:10240
	s_waitcnt lgkmcnt(2)
	v_pk_add_f32 v[28:29], v[28:29], v[10:11]
	v_pk_add_f32 v[30:31], v[30:31], v[8:9]
	s_waitcnt lgkmcnt(1)
	v_pk_add_f32 v[32:33], v[32:33], v[14:15]
	ds_read_b128 v[8:11], v6 offset:11264
	v_pk_add_f32 v[26:27], v[26:27], v[12:13]
	ds_read_b128 v[12:15], v6 offset:12288
	s_waitcnt lgkmcnt(2)
	v_pk_add_f32 v[24:25], v[28:29], v[24:25]
	v_pk_add_f32 v[28:29], v[30:31], v[22:23]
	s_waitcnt lgkmcnt(1)
	v_pk_add_f32 v[30:31], v[32:33], v[10:11]
	v_pk_add_f32 v[32:33], v[26:27], v[8:9]
	ds_read_b128 v[8:11], v6 offset:13312
	s_waitcnt lgkmcnt(1)
	v_pk_add_f32 v[14:15], v[24:25], v[14:15]
	ds_read_b128 v[22:25], v6 offset:14336
	v_pk_add_f32 v[12:13], v[28:29], v[12:13]
	ds_read_b128 v[26:29], v6 offset:15360
	s_and_b32 s8, s16, 0x70
	s_add_i32 s27, s28, -8
	s_waitcnt lgkmcnt(2)
	v_pk_add_f32 v[30:31], v[30:31], v[10:11]
	s_waitcnt lgkmcnt(1)
	v_pk_add_f32 v[10:11], v[14:15], v[24:25]
	v_pk_add_f32 v[14:15], v[12:13], v[22:23]
	v_or_b32_e32 v22, s8, v18
	s_and_b32 s8, s27, 0xffffffe0
	v_pk_add_f32 v[32:33], v[32:33], v[8:9]
	v_or_b32_e32 v21, s8, v16
	s_waitcnt lgkmcnt(0)
	v_pk_add_f32 v[8:9], v[30:31], v[28:29]
	v_pk_add_f32 v[12:13], v[32:33], v[26:27]
	v_cmp_lt_i32_e32 vcc, s24, v21
	s_and_saveexec_b64 s[8:9], vcc
	s_xor_b64 s[8:9], exec, s[8:9]
	s_cbranch_execz .LBB0_305
	s_cmpk_gt_u32 s27, 0x7ff
	s_mov_b64 s[10:11], -1
	s_cbranch_scc0 .LBB0_303
	s_addk_i32 s28, 0xf7f8
	s_lshr_b32 s10, s28, 10
	s_mul_hi_u32 s11, s10, 0x2040000
	s_mul_i32 s10, s10, 0x2040000
	s_add_u32 s10, s14, s10
	v_and_b32_e32 v23, 0x3f8, v21
	s_addc_u32 s11, s15, s11
	v_lshlrev_b32_e32 v6, 11, v22
	v_lshl_add_u64 v[28:29], s[10:11], 0, v[6:7]
	v_lshlrev_b32_e32 v6, 1, v23
	v_lshl_add_u64 v[28:29], v[28:29], 0, v[6:7]
	v_cvt_pk_bf16_f32 v24, v14, v15
	v_cvt_pk_bf16_f32 v25, v10, v11
	v_cvt_pk_bf16_f32 v26, v12, v13
	v_cvt_pk_bf16_f32 v27, v8, v9
	global_store_dwordx4 v[28:29], v[24:27], off
	s_mov_b64 s[10:11], 0
